# P3: odd workgroups run neighbourhood attention before the long-conv units (VALU-bound and MFMA-bound work overlap across CUs)
# speedup vs baseline: 1.1031x; 1.0140x over previous
; #define LAS __attribute__((address_space(3)))
; DI bf16 f2bf(float f) { return (bf16)(pk2(f, 0.f) & 0xffffu); }
; template <int L, int NB>
; DI void conv_unit(const Frame& F, int c, const bf16* FRg, const float* F0, const float* hyD, const bf16* UT, bf16* YT, int tok0, bool dry) {
;     constexpr int RS = L / 32, LOGRS = (RS == 512 ? 9 : 7), JB = 32 / NB, WN = (NB == 1 ? 2560 : 640), WCH = WN / 8, WSTEPS = (NB == 1 ? 120 : 24), BST = (NB == 1 ? 5120 : 1408)  ;
;     constexpr int NSTEPS = (L + RS) / 16, NWIN = (NSTEPS + WSTEPS - 1) / WSTEPS;
;     static_assert(NB * WCH == 320 && WSTEPS % 6 == 0 && (NSTEPS % WSTEPS) % 6 == 0, "window chunks / steps");
;     LAS unsigned char* fr = F.lds; LAS unsigned char* uw = F.lds + CONV_FR_MAX + F.wave * 5632;
;     const int lane = F.lane, wave = F.wave, r32 = lane & 31, hh = lane >> 5;
;     const bf16* ubase = UT + (size_t)c * MTOK;
;     const u32x4 z4 = {0u, 0u, 0u, 0u};
;     u32x4 lo[5], hi[5];
;     ...
;     CONV_ISSUE(0);
;     {
;         const bf16* frow = FRg + (size_t)c * 2 * L;
;         for (int ch = F.tid; ch < 2 * L / 8; ch += 512) { const u32x4 v = *(const u32x4*)(frow + 8 * ch); const int x0 = 8 * ch; *(LAS u32x4*)(fr + 2 * x0 + ((x0 >> LOGRS) << 4)) = v; }
;         __syncthreads();
;         if (F.tid == 0) *(LAS bf16*)(fr + 2 * L + ((L >> LOGRS) << 4)) = f2bf(F0[c] + F0[512 + c] + hyD[c]);
;         __syncthreads();
;     }
;     f32x16 acc0, acc1;
; #pragma unroll
;     for (int i = 0; i < 16; ++i) { acc0[i] = 0.f; acc1[i] = 0.f; }
;     const int jj = r32 % JB, bb = r32 / JB;
;     const int xA0 = L - RS * r32 + 8 * hh - RS;
;     const LAS unsigned char* ubp0 = uw + bb * BST + hh * WN + 16 * jj;
;     const LAS unsigned char* ubp1 = uw + bb * BST + (1 - hh) * WN + 16 * (jj + hh);
; __global__ void __launch_bounds__(512, 2) hybrid_fwd(Args args) {
;     ...
;         if (sub & 1) for (int cu = F.bid; cu < 1024; cu += F.G) {
;             if (cu < 512) conv_unit<16384, 1>(F, cu, FRS, F0 + 1024, args.in[15], UT, UT, TOKP, dry);
;             else conv_unit<4096, 4>(F, cu - 512, FRP, F0, args.in[15], UT, UT, 0, dry);
.LBB0_753:
	v_mov_b32_e32 v247, 1
	s_cmp_lt_i32 s84, 4
	s_cselect_b64 s[2:3], -1, 0
	s_and_b64 s[0:1], s[2:3], s[0:1]
	v_writelane_b32 v246, s0, 34
	s_andn2_b64 vcc, exec, s[0:1]
	s_nop 0
	v_writelane_b32 v246, s1, 35
	s_cbranch_vccnz .LBB0_1110
	v_writelane_b32 v246, s96, 30
	s_cmpk_gt_i32 s33, 0x3ff
	s_nop 0
	v_writelane_b32 v246, s97, 31
	v_writelane_b32 v246, s87, 36
	v_writelane_b32 v246, s94, 37
	s_nop 1
	v_writelane_b32 v246, s95, 38
	v_writelane_b32 v246, s84, 39
	s_nop 1
	v_writelane_b32 v246, s85, 40
	s_cbranch_scc1 .LBB0_1054
	v_mov_b32_e32 v247, 0
	s_bitcmp1_b32 s33, 0
	s_cbranch_scc1 .LBB0_1054
.Lp3_conv_start:
	v_or_b32_e32 v0, 64, v148
	s_mov_b32 s1, 0x3333334
	v_or_b32_e32 v4, 0x80, v148
	v_or_b32_e32 v10, 0xc0, v148
	v_mul_hi_u32 v2, v0, s1
	v_mul_hi_u32 v6, v4, s1
	v_mul_hi_u32 v12, v10, s1
	v_mul_u32_u24_e32 v5, 0x50, v2
	v_mul_u32_u24_e32 v9, 0x50, v6
	v_mul_u32_u24_e32 v13, 0x50, v12
	v_readlane_b32 s22, v246, 29
	v_sub_u32_e32 v0, v0, v5
	v_sub_u32_e32 v4, v4, v9
	v_sub_u32_e32 v10, v10, v13
	s_mul_i32 s26, s22, 0x1600
	s_movk_i32 s0, 0xff80
	v_lshlrev_b32_e32 v3, 3, v0
	v_lshlrev_b32_e32 v7, 12, v2
	v_lshlrev_b32_e32 v8, 3, v4
	v_lshlrev_b32_e32 v11, 12, v6
	v_lshlrev_b32_e32 v14, 3, v10
	v_lshlrev_b32_e32 v15, 12, v12
	v_add3_u32 v153, v3, v7, s0
	v_add3_u32 v156, v8, v11, s0
	v_add3_u32 v157, v14, v15, s0
	s_add_i32 s0, s26, 0
	s_add_i32 s24, s0, 0x10400
	v_lshrrev_b32_e32 v19, 5, v148
	v_bfe_u32 v21, v150, 3, 2
	s_movk_i32 s0, 0x580
	v_mov_b32_e32 v23, s24
	v_mad_u32_u24 v24, v21, s0, v23
	s_movk_i32 s0, 0x280
	v_xor_b32_e32 v27, 1, v19
	v_mad_u32_u24 v25, v19, s0, v24
	v_mad_u32_u24 v24, v27, s0, v24
	v_readlane_b32 s0, v246, 18
	s_cmpk_gt_u32 s0, 0x7f
	v_cmp_lt_u32_e64 s[6:7], 15, v0
	v_cmp_lt_u32_e64 s[8:9], 14, v0
	v_or_b32_e32 v16, 0x100, v148
	s_cselect_b64 s[42:43], -1, 0
	s_bitcmp1_b32 s0, 6
	v_and_b32_e32 v0, 1, v0
	v_mul_hi_u32 v17, v16, s1
	s_cselect_b64 s[44:45], -1, 0
	s_lshr_b32 s70, s0, 7
	v_mov_b32_e32 v32, 0x280
	v_cmp_eq_u32_e64 s[0:1], 1, v0
	v_mul_u32_u24_e32 v2, 0x580, v2
	v_mul_u32_u24_e32 v18, 0x50, v17
	v_cndmask_b32_e64 v0, 0, v32, s[0:1]
	v_add3_u32 v33, s24, v2, v0
	v_and_b32_e32 v2, 1, v4
	v_cmp_eq_u32_e64 s[0:1], 1, v2
	v_mul_u32_u24_e32 v0, 0x580, v6
	v_sub_u32_e32 v16, v16, v18
	v_cndmask_b32_e64 v2, 0, v32, s[0:1]
	v_add3_u32 v35, s24, v0, v2
	v_and_b32_e32 v2, 1, v10
	v_cmp_eq_u32_e64 s[0:1], 1, v2
	v_mul_u32_u24_e32 v0, 0x580, v12
	v_and_b32_e32 v1, 31, v150
	v_cndmask_b32_e64 v2, 0, v32, s[0:1]
	v_add3_u32 v37, s24, v0, v2
	v_and_b32_e32 v0, 1, v16
	v_lshlrev_b32_e32 v22, 3, v19
	v_lshlrev_b32_e32 v29, 7, v1
	v_and_b32_e32 v31, 1, v150
	v_cmp_eq_u32_e64 s[0:1], 1, v0
	v_sub_u32_e32 v29, v22, v29
	v_cmp_eq_u32_e32 vcc, 1, v31
	v_cndmask_b32_e64 v0, 0, v32, s[0:1]
	v_and_b32_e32 v34, 0x3f0, v3
	v_cndmask_b32_e32 v31, 0, v32, vcc
	v_add_u32_e32 v32, s24, v0
	v_add_u32_e32 v0, 0x1e80, v29
	v_lshl_add_u32 v39, v0, 1, 0
	v_lshrrev_b32_e32 v0, 3, v0
	v_and_b32_e32 v40, 0x1ffffff0, v0
	v_add_u32_e32 v0, 0x1ea0, v29
	v_lshl_add_u32 v41, v0, 1, 0
	v_lshrrev_b32_e32 v0, 3, v0
	v_and_b32_e32 v42, 0x1ffffff0, v0
	v_add_u32_e32 v0, 0x1ec0, v29
	v_lshl_add_u32 v43, v0, 1, 0
	v_lshrrev_b32_e32 v0, 3, v0
	v_and_b32_e32 v44, 0x1ffffff0, v0
	v_add_u32_e32 v0, 0x1ee0, v29
	v_lshl_add_u32 v45, v0, 1, 0
	v_lshrrev_b32_e32 v0, 3, v0
	v_and_b32_e32 v46, 0x1ffffff0, v0
	v_add_u32_e32 v0, 0x1f00, v29
	v_lshl_add_u32 v47, v0, 1, 0
	v_lshrrev_b32_e32 v0, 3, v0
	v_and_b32_e32 v48, 0x1ffffff0, v0
	v_add_u32_e32 v0, 0x1f20, v29
	v_lshl_add_u32 v49, v0, 1, 0
	v_lshrrev_b32_e32 v0, 3, v0
	v_and_b32_e32 v50, 0x1ffffff0, v0
	v_add_u32_e32 v0, 0x1f40, v29
	v_lshl_add_u32 v51, v0, 1, 0
	v_lshrrev_b32_e32 v0, 3, v0
	v_and_b32_e32 v52, 0x1ffffff0, v0
	v_add_u32_e32 v0, 0x1f60, v29
	v_lshl_add_u32 v53, v0, 1, 0
	v_lshrrev_b32_e32 v0, 3, v0
	v_and_b32_e32 v54, 0x1ffffff0, v0
	v_add_u32_e32 v0, 0x1f80, v29
	v_lshl_add_u32 v55, v0, 1, 0
	v_lshrrev_b32_e32 v0, 3, v0
	v_and_b32_e32 v56, 0x1ffffff0, v0
	v_add_u32_e32 v0, 0x1fa0, v29
	v_lshl_add_u32 v57, v0, 1, 0
	v_lshrrev_b32_e32 v0, 3, v0
	v_and_b32_e32 v58, 0x1ffffff0, v0
	v_add_u32_e32 v0, 0x1fc0, v29
	v_lshl_add_u32 v59, v0, 1, 0
	v_lshrrev_b32_e32 v0, 3, v0
	v_and_b32_e32 v60, 0x1ffffff0, v0
	v_add_u32_e32 v0, 0x1fe0, v29
	v_lshl_add_u32 v61, v0, 1, 0
	v_lshrrev_b32_e32 v0, 3, v0
	v_lshrrev_b32_e32 v3, 2, v150
	v_and_b32_e32 v20, 7, v150
	v_and_b32_e32 v62, 0x1ffffff0, v0
	v_lshlrev_b32_e32 v0, 13, v21
	v_lshlrev_b32_e32 v2, 10, v19
	v_and_b32_e32 v68, 0xf0, v3
	v_add_u32_e32 v3, 0x200, v150
	v_cmp_lt_u32_e64 s[10:11], 15, v4
	v_cmp_lt_u32_e64 s[12:13], 14, v4
	v_add3_u32 v0, 0, v0, v2
	v_lshlrev_b32_e32 v2, 5, v20
	s_lshl_b32 s0, s22, 1
	v_lshlrev_b32_e32 v4, 3, v3
	v_lshl_add_u32 v69, v3, 4, 0
	v_lshrrev_b32_e32 v3, 2, v3
	v_add3_u32 v160, v0, v2, s0
	v_mov_b32_e32 v0, 0xa00
	v_and_b32_e32 v70, 0x1f0, v3
	v_or_b32_e32 v3, 0x400, v150
	v_cndmask_b32_e32 v0, 0, v0, vcc
	v_lshlrev_b32_e32 v6, 3, v3
	v_lshl_add_u32 v71, v3, 4, 0
	v_lshrrev_b32_e32 v3, 2, v3
	v_lshlrev_b32_e32 v149, 3, v148
	s_movk_i32 s25, 0x3f0
	v_add_u32_e32 v165, s24, v0
	v_mov_b32_e32 v0, 0x200
	v_and_b32_e32 v72, 0x1f0, v3
	v_add_u32_e32 v3, 0x600, v150
	v_and_b32_e32 v36, 0x3f0, v8
	v_bitop3_b32 v64, v149, s25, v0 bitop3:0xc8
	s_movk_i32 s1, 0x5f0
	v_mov_b32_e32 v0, 0x400
	v_lshlrev_b32_e32 v8, 3, v3
	v_lshl_add_u32 v73, v3, 4, 0
	v_lshrrev_b32_e32 v3, 2, v3
	v_bitop3_b32 v65, v149, s1, v0 bitop3:0xc8
	s_movk_i32 s1, 0x7f0
	v_mov_b32_e32 v0, 0x600
	v_and_b32_e32 v74, 0x3f0, v3
	v_or_b32_e32 v3, 0x800, v150
	v_cmp_lt_u32_e64 s[14:15], 15, v10
	v_cmp_lt_u32_e64 s[16:17], 14, v10
; #define LAS __attribute__((address_space(3)))
; DI bf16 f2bf(float f) { return (bf16)(pk2(f, 0.f) & 0xffffu); }
; template <int L, int NB>
; DI void conv_unit(const Frame& F, int c, const bf16* FRg, const float* F0, const float* hyD, const bf16* UT, bf16* YT, int tok0, bool dry) {
;     constexpr int RS = L / 32, LOGRS = (RS == 512 ? 9 : 7), JB = 32 / NB, WN = (NB == 1 ? 2560 : 640), WCH = WN / 8, WSTEPS = (NB == 1 ? 120 : 24), BST = (NB == 1 ? 5120 : 1408)  ;
;     constexpr int NSTEPS = (L + RS) / 16, NWIN = (NSTEPS + WSTEPS - 1) / WSTEPS;
;     static_assert(NB * WCH == 320 && WSTEPS % 6 == 0 && (NSTEPS % WSTEPS) % 6 == 0, "window chunks / steps");
;     LAS unsigned char* fr = F.lds; LAS unsigned char* uw = F.lds + CONV_FR_MAX + F.wave * 5632;
;     const int lane = F.lane, wave = F.wave, r32 = lane & 31, hh = lane >> 5;
;     const bf16* ubase = UT + (size_t)c * MTOK;
;     const u32x4 z4 = {0u, 0u, 0u, 0u};
;     u32x4 lo[5], hi[5];
;     ...
;     CONV_ISSUE(0);
;     {
;         const bf16* frow = FRg + (size_t)c * 2 * L;
;         for (int ch = F.tid; ch < 2 * L / 8; ch += 512) { const u32x4 v = *(const u32x4*)(frow + 8 * ch); const int x0 = 8 * ch; *(LAS u32x4*)(fr + 2 * x0 + ((x0 >> LOGRS) << 4)) = v; }
;         __syncthreads();
;         if (F.tid == 0) *(LAS bf16*)(fr + 2 * L + ((L >> LOGRS) << 4)) = f2bf(F0[c] + F0[512 + c] + hyD[c]);
;         __syncthreads();
;     }
;     f32x16 acc0, acc1;
; #pragma unroll
;     for (int i = 0; i < 16; ++i) { acc0[i] = 0.f; acc1[i] = 0.f; }
;     const int jj = r32 % JB, bb = r32 / JB;
;     const int xA0 = L - RS * r32 + 8 * hh - RS;
;     const LAS unsigned char* ubp0 = uw + bb * BST + hh * WN + 16 * jj;
;     const LAS unsigned char* ubp1 = uw + bb * BST + (1 - hh) * WN + 16 * (jj + hh);
	v_bitop3_b32 v66, v149, s1, v0 bitop3:0xc8
	s_movk_i32 s1, 0x9f0
	v_mov_b32_e32 v0, 0x800
	v_lshlrev_b32_e32 v10, 3, v3
	v_lshl_add_u32 v75, v3, 4, 0
	v_lshrrev_b32_e32 v3, 2, v3
	v_bitop3_b32 v67, v149, s1, v0 bitop3:0xc8
	v_lshlrev_b32_e32 v0, 9, v1
	v_and_b32_e32 v76, 0x2f0, v3
	v_add_u32_e32 v3, 0xa00, v150
	v_sub_u32_e32 v22, v22, v0
	v_lshl_add_u32 v0, v19, 12, 0
	v_lshlrev_b32_e32 v2, 5, v1
	v_lshlrev_b32_e32 v12, 3, v3
	v_lshl_add_u32 v77, v3, 4, 0
	v_lshrrev_b32_e32 v3, 2, v3
	v_add3_u32 v167, v0, v2, s0
	v_and_b32_e32 v78, 0x3f0, v3
	v_or_b32_e32 v3, 0xc00, v150
	s_movk_i32 s0, 0xe00
	v_lshlrev_b32_e32 v18, 3, v16
	v_cmp_lt_u32_e64 s[18:19], 15, v16
	v_cmp_lt_u32_e64 s[20:21], 14, v16
	v_add_u32_e32 v31, s24, v31
	v_and_b32_e32 v38, 0x3f0, v14
	v_lshlrev_b32_e32 v14, 3, v3
	v_lshl_add_u32 v79, v3, 4, 0
	v_lshrrev_b32_e32 v16, 2, v3
	v_cmp_gt_u32_e64 s[24:25], s0, v3
	v_add_u32_e32 v3, 0xe00, v150
	v_and_b32_e32 v80, 0x3f0, v16
	v_lshlrev_b32_e32 v16, 3, v3
	v_lshl_add_u32 v81, v3, 4, 0
	v_lshrrev_b32_e32 v3, 2, v3
	v_mov_b32_e32 v0, 0
	v_lshlrev_b32_e32 v2, 4, v150
	v_and_b32_e32 v82, 0x7f0, v3
	v_and_b32_e32 v3, 0x3f0, v150
	v_add3_u32 v170, v2, v3, 0
	v_mov_b32_e32 v3, v0
	v_add_u32_e32 v30, 0xf80, v29
	v_add_u32_e32 v168, 0, v2
	v_lshl_add_u64 v[2:3], s[82:83], 0, v[2:3]
	s_mov_b64 s[0:1], 0xc000000
	v_lshl_add_u64 v[154:155], v[2:3], 0, s[0:1]
	v_lshrrev_b32_e32 v2, 3, v30
	v_and_b32_e32 v171, 0x1ffffff0, v2
	v_lshlrev_b32_e32 v2, 4, v19
	v_add_u32_e32 v3, v171, v2
	v_lshlrev_b32_e32 v30, 8, v1
	v_sub_u32_e32 v3, v3, v30
	v_add_u32_e32 v172, 0x1f00, v3
	v_add_u32_e32 v3, 0x10e0, v29
	v_lshrrev_b32_e32 v3, 3, v3
	v_and_b32_e32 v3, 0x3f0, v3
	v_add_u32_e32 v3, v3, v2
	v_sub_u32_e32 v3, v3, v30
	v_add_u32_e32 v173, 0x21c0, v3
	v_add_u32_e32 v3, 0x10c0, v29
	v_lshrrev_b32_e32 v3, 3, v3
	v_and_b32_e32 v3, 0x3f0, v3
	v_add_u32_e32 v3, v3, v2
	v_sub_u32_e32 v3, v3, v30
	v_add_u32_e32 v175, 0x2180, v3
	v_add_u32_e32 v3, 0x10a0, v29
	v_lshrrev_b32_e32 v3, 3, v3
	v_and_b32_e32 v3, 0x3f0, v3
	v_add_u32_e32 v3, v3, v2
	v_sub_u32_e32 v3, v3, v30
	v_add_u32_e32 v176, 0x2140, v3
	v_add_u32_e32 v3, 0x1080, v29
	v_lshrrev_b32_e32 v3, 3, v3
	v_and_b32_e32 v3, 0x3f0, v3
	v_add_u32_e32 v3, v3, v2
	v_sub_u32_e32 v3, v3, v30
	v_add_u32_e32 v177, 0x2100, v3
	v_add_u32_e32 v3, 0x1060, v29
	v_lshrrev_b32_e32 v3, 3, v3
	v_and_b32_e32 v3, 0x3f0, v3
	v_add_u32_e32 v3, v3, v2
	v_sub_u32_e32 v3, v3, v30
	v_add_u32_e32 v178, 0x20c0, v3
	v_add_u32_e32 v3, 0x1040, v29
	v_lshrrev_b32_e32 v3, 3, v3
	v_and_b32_e32 v3, 0x3f0, v3
	v_add_u32_e32 v3, v3, v2
	v_sub_u32_e32 v3, v3, v30
	v_add_u32_e32 v179, 0x2080, v3
	v_add_u32_e32 v3, 0x1020, v29
	v_lshrrev_b32_e32 v3, 3, v3
	v_and_b32_e32 v3, 0x3f0, v3
	v_add_u32_e32 v3, v3, v2
	v_sub_u32_e32 v3, v3, v30
	v_add_u32_e32 v180, 0x2040, v3
	v_add_u32_e32 v3, 0x1000, v29
	v_lshrrev_b32_e32 v3, 3, v3
	v_and_b32_e32 v3, 0x3f0, v3
	s_add_u32 s94, s82, 0x61000
	v_add_u32_e32 v3, v3, v2
	s_addc_u32 s95, s83, 0
	v_sub_u32_e32 v3, v3, v30
	s_lshl_b32 s1, s33, 7
	v_add_u32_e32 v181, 0x2000, v3
	v_mul_u32_u24_e32 v3, 0x280, v17
	v_add_u32_e32 v183, s1, v149
	s_movk_i32 s27, 0xa00
	v_sub_u32_e32 v182, v149, v3
	v_sub_u32_e32 v184, v183, v3
	v_lshlrev_b32_e32 v3, 3, v13
	v_add_u32_e32 v13, v183, v15
	v_lshlrev_b32_e32 v26, 4, v20
	v_add_lshl_u32 v28, v19, v20, 4
	v_mad_u32_u24 v20, v19, s27, v23
	v_lshlrev_b32_e32 v21, 4, v1
	v_mul_u32_u24_e32 v63, 0xa00, v27
	v_mad_u32_u24 v23, v27, s27, v23
	v_add_lshl_u32 v27, v19, v1, 4
	v_sub_u32_e32 v185, v149, v3
	v_sub_u32_e32 v186, v13, v3
	v_lshlrev_b32_e32 v3, 3, v9
	v_add_u32_e32 v9, v183, v11
	v_lshlrev_b32_e32 v1, 10, v1
	v_sub_u32_e32 v187, v149, v3
	v_sub_u32_e32 v188, v9, v3
	v_lshlrev_b32_e32 v3, 3, v5
	v_add_u32_e32 v5, v183, v7
	v_sub_u32_e32 v192, v2, v1
	v_mov_b32_e32 v1, s26
	v_add_u32_e32 v158, 0x2f80, v18
	v_and_b32_e32 v159, 0x1f0, v149
	v_and_b32_e32 v18, 0x3f0, v18
	v_sub_u32_e32 v189, v149, v3
	v_sub_u32_e32 v190, v5, v3
	v_add_u32_e32 v3, s1, v152
	v_mad_u32_u24 v1, v19, s27, v1
	v_add_u32_e32 v151, 0xffffff80, v149
	v_cmp_lt_u32_e64 s[2:3], 15, v148
	v_cmp_lt_u32_e64 s[4:5], 14, v148
	s_mov_b32 s36, 0
	v_cmp_eq_u32_e64 s[22:23], 63, v148
	v_or_b32_e32 v161, 0x200, v149
	v_or_b32_e32 v162, 0x400, v149
	v_or_b32_e32 v163, 0x600, v149
	v_or_b32_e32 v164, 0x800, v149
	v_add_u32_e32 v166, 0x3e00, v22
	v_add_u32_e32 v169, 0xfffffe00, v150
	s_add_i32 s0, s33, 0xfffffe00
	v_sub_u32_e32 v174, v2, v30
	s_movk_i32 s87, 0x1000
	s_lshl_b32 s71, s89, 7
	v_add_u32_e32 v191, 0xffff0000, v3
	v_add_u32_e32 v193, 0x3e80, v22
	v_add3_u32 v194, v63, s26, v27
	v_or_b32_e32 v195, v1, v21
	s_mov_b32 s97, 0x1000706
	s_movk_i32 s84, 0xff8
	v_add_u32_e32 v196, v39, v40
	v_add_u32_e32 v197, v41, v42
	v_add_u32_e32 v198, v43, v44
	v_add_u32_e32 v199, v45, v46
	v_add_u32_e32 v200, v47, v48
	v_add_u32_e32 v201, v49, v50
	v_add_u32_e32 v202, v51, v52
	v_add_u32_e32 v203, v53, v54
	v_add_u32_e32 v204, v55, v56
	v_add_u32_e32 v205, v57, v58
	v_add_u32_e32 v206, v59, v60
	v_add_u32_e32 v207, v61, v62
	s_movk_i32 s85, 0x5ff
	s_movk_i32 s50, 0x4000
	v_lshlrev_b32_e32 v208, 1, v152
	v_add_u32_e32 v209, v168, v68
	v_lshlrev_b32_e32 v210, 1, v4
	v_add_u32_e32 v211, v69, v70
	v_lshlrev_b32_e32 v212, 1, v6
	v_add_u32_e32 v213, v71, v72
	v_lshlrev_b32_e32 v214, 1, v8
	v_add_u32_e32 v215, v73, v74
	v_lshlrev_b32_e32 v216, 1, v10
	v_add_u32_e32 v217, v75, v76
	v_lshlrev_b32_e32 v218, 1, v12
	v_add_u32_e32 v219, v77, v78
	v_lshlrev_b32_e32 v220, 1, v14
	v_add_u32_e32 v221, v79, v80
	v_lshlrev_b32_e32 v222, 1, v16
	v_add_u32_e32 v223, v81, v82
	v_add_u32_e32 v224, v165, v64
	v_add_u32_e32 v225, v165, v65
	v_add_u32_e32 v226, v165, v66
	v_add_u32_e32 v227, v165, v67
	s_movk_i32 s51, 0x3ff8
	v_add_u32_e32 v228, v20, v21
	v_add_u32_e32 v229, v23, v27
	v_add_u32_e32 v230, v31, v159
	v_add_u32_e32 v231, v33, v34
	v_add_u32_e32 v232, v35, v36
	v_add_u32_e32 v233, v37, v38
	v_add_u32_e32 v234, v32, v18
	v_add_u32_e32 v235, v25, v26
	v_add_u32_e32 v236, v24, v28
	s_mov_b32 s78, s33
	s_branch .LBB0_757

; #define LAS __attribute__((address_space(3)))
; __global__ void __launch_bounds__(512, 2) hybrid_fwd(Args args) {
;     ...
;         __syncthreads();
;         int cur_head = -1; LAS float* tab = (LAS float*)(F.lds + F.wave * 2560); LAS unsigned char* wl = F.lds + 20480 + F.wave * ATT_WAVE_LDS;
;         if (sub & 2) {
;             if ((F.G & 7) == 0) {
;                 const int h = F.bid & 7, NWV = (F.G >> 3) * 8;
;                 for (int e = (F.bid >> 3) * 8 + F.wave; e < 1024; e += NWV)
;                     attn_unit(e >> 1, h, e & 1, Qb, Kb, VT, Qb, args.in[4], tab, wl, F.lane, cur_head, dry);
.LBB0_1054:
	v_cmp_ne_u32_e32 vcc, 0, v247
	s_cbranch_vccz .Lp3_attn
	v_readlane_b32 s84, v246, 39
	v_readlane_b32 s94, v246, 37
	v_readlane_b32 s96, v246, 30
	v_readlane_b32 s78, v246, 21
	v_readlane_b32 s85, v246, 40
	v_readlane_b32 s95, v246, 38
	v_readlane_b32 s87, v246, 36
	v_readlane_b32 s97, v246, 31
	v_readlane_b32 s79, v246, 22
	s_branch .LBB0_1110

; #define LAS __attribute__((address_space(3)))
; __global__ void __launch_bounds__(512, 2) hybrid_fwd(Args args) {
;     ...
;     DUP_BEGIN(3) if (IN(3)) {
;         if (sub & 1) for (int cu = F.bid; cu < 1024; cu += F.G) {
;             if (cu < 512) conv_unit<16384, 1>(F, cu, FRS, F0 + 1024, args.in[15], UT, UT, TOKP, dry);
;             else conv_unit<4096, 4>(F, cu - 512, FRP, F0, args.in[15], UT, UT, 0, dry);
;         }
;         __syncthreads();
;         int cur_head = -1; LAS float* tab = (LAS float*)(F.lds + F.wave * 2560); LAS unsigned char* wl = F.lds + 20480 + F.wave * ATT_WAVE_LDS;
;         if (sub & 2) {
;             if ((F.G & 7) == 0) {
;                 const int h = F.bid & 7, NWV = (F.G >> 3) * 8;
;                 for (int e = (F.bid >> 3) * 8 + F.wave; e < 1024; e += NWV)
;                     attn_unit(e >> 1, h, e & 1, Qb, Kb, VT, Qb, args.in[4], tab, wl, F.lane, cur_head, dry);
;             } else {
;                 for (int u = gw; u < 8192; u += NGW) attn_unit(u >> 4, (u >> 1) & 7, u & 1, Qb, Kb, VT, Qb, args.in[4], tab, wl, F.lane, cur_head, dry);
;             }
;         }
;     }
.LBB0_1110:
	v_cmp_ne_u32_e32 vcc, 0, v247
	s_cbranch_vccnz .Lp3_done
	s_bitcmp1_b32 s33, 0
	s_cbranch_scc0 .Lp3_done
	v_mov_b32_e32 v247, 1
	s_sub_u32 s0, s96, 0xd8
	s_subb_u32 s1, s97, 0
	s_load_dwordx2 s[30:31], s[0:1], 0x78
	s_add_u32 s34, s82, 0x60000
	s_addc_u32 s35, s83, 0
	s_add_u32 s40, s82, 0xc800000
	s_addc_u32 s41, s83, 0
	s_waitcnt vmcnt(0) lgkmcnt(0)
	s_barrier
	s_branch .Lp3_conv_start
